# MLA loop LDS-DMA addressing moved to SALU: hoisted per-lane byte offsets with saddr-form global_load_lds, M0 from SGPR adds
# speedup vs baseline: 1.0145x; 1.0005x over previous
.LBB0_221:
	v_exp_f32_e32 v151, v64
	v_exp_f32_e32 v150, v80
	v_exp_f32_e32 v65, v65
	v_exp_f32_e32 v64, v81
	v_add_f32_e32 v142, 0, v158
	v_add_f32_e32 v143, 0, v159
	v_exp_f32_e32 v159, v66
	v_exp_f32_e32 v158, v82
	v_exp_f32_e32 v67, v67
	v_exp_f32_e32 v66, v83
	v_pk_add_f32 v[80:81], v[150:151], 0 op_sel_hi:[1,0]
	v_exp_f32_e32 v83, v68
	v_exp_f32_e32 v82, v84
	v_add_f32_e32 v142, v160, v142
	v_add_f32_e32 v143, v161, v143
	v_pk_add_f32 v[80:81], v[64:65], v[80:81]
	v_exp_f32_e32 v161, v69
	v_exp_f32_e32 v160, v85
	v_pk_add_f32 v[80:81], v[158:159], v[80:81]
	v_exp_f32_e32 v85, v70
	v_exp_f32_e32 v84, v86
	v_add_f32_e32 v142, v162, v142
	v_add_f32_e32 v143, v163, v143
	v_pk_add_f32 v[80:81], v[66:67], v[80:81]
	v_exp_f32_e32 v163, v71
	v_exp_f32_e32 v162, v87
	v_exp_f32_e32 v87, v72
	v_exp_f32_e32 v86, v88
	v_pk_add_f32 v[68:69], v[82:83], v[80:81]
	v_add_f32_e32 v142, v164, v142
	v_add_f32_e32 v143, v165, v143
	v_exp_f32_e32 v165, v73
	v_exp_f32_e32 v164, v89
	v_pk_add_f32 v[68:69], v[160:161], v[68:69]
	v_exp_f32_e32 v89, v74
	v_exp_f32_e32 v88, v90
	v_pk_add_f32 v[68:69], v[84:85], v[68:69]
	v_add_f32_e32 v142, v166, v142
	v_add_f32_e32 v143, v167, v143
	v_exp_f32_e32 v167, v75
	v_exp_f32_e32 v166, v91
	v_pk_add_f32 v[68:69], v[162:163], v[68:69]
	v_exp_f32_e32 v91, v76
	v_exp_f32_e32 v90, v92
	v_pk_add_f32 v[68:69], v[86:87], v[68:69]
	v_add_f32_e32 v142, v168, v142
	v_add_f32_e32 v143, v169, v143
	v_exp_f32_e32 v169, v77
	v_exp_f32_e32 v168, v93
	v_pk_add_f32 v[68:69], v[164:165], v[68:69]
	v_exp_f32_e32 v93, v78
	v_exp_f32_e32 v92, v94
	v_pk_add_f32 v[68:69], v[88:89], v[68:69]
	v_add_f32_e32 v142, v170, v142
	v_add_f32_e32 v143, v171, v143
	v_exp_f32_e32 v171, v79
	v_exp_f32_e32 v170, v95
	v_pk_add_f32 v[68:69], v[166:167], v[68:69]
	v_cvt_pk_bf16_f32 v76, v151, v65
	v_pk_add_f32 v[68:69], v[90:91], v[68:69]
	v_cvt_pk_bf16_f32 v78, v83, v161
	v_pk_add_f32 v[68:69], v[168:169], v[68:69]
	v_cvt_pk_bf16_f32 v79, v85, v163
	v_pk_add_f32 v[68:69], v[92:93], v[68:69]
	v_cvt_pk_bf16_f32 v70, v82, v160
	v_pk_add_f32 v[68:69], v[170:171], v[68:69]
	v_cvt_pk_bf16_f32 v71, v84, v162
	v_add_f32_e32 v80, v68, v69
	v_cvt_pk_bf16_f32 v68, v150, v64
	v_cvt_pk_bf16_f32 v72, v87, v165
	v_cvt_pk_bf16_f32 v73, v89, v167
	v_cvt_pk_bf16_f32 v64, v86, v164
	v_cvt_pk_bf16_f32 v65, v88, v166
	ds_read_b128 v[82:85], v157 offset:32768
	ds_read_b128 v[86:89], v157 offset:36864
	v_cvt_pk_bf16_f32 v77, v159, v67
	v_cvt_pk_bf16_f32 v74, v91, v169
	v_cvt_pk_bf16_f32 v75, v93, v171
	s_waitcnt lgkmcnt(0)
	v_mfma_f32_32x32x16_bf16 v[16:31], v[82:85], v[76:79], v[16:31]
	ds_read_b128 v[82:85], v156 offset:36864
	v_cvt_pk_bf16_f32 v69, v158, v66
	v_add_f32_e32 v142, v172, v142
	v_add_f32_e32 v143, v173, v143
	v_add_f32_e32 v142, v174, v142
	v_add_f32_e32 v143, v175, v143
	v_add_f32_e32 v142, v176, v142
	v_mfma_f32_32x32x16_bf16 v[0:15], v[86:89], v[76:79], v[0:15]
	ds_read_b128 v[76:79], v156 offset:32768
	v_add_f32_e32 v143, v177, v143
	v_add_f32_e32 v142, v178, v142
	v_add_f32_e32 v143, v179, v143
	v_cvt_pk_bf16_f32 v66, v90, v168
	v_cvt_pk_bf16_f32 v67, v92, v170
	v_add_f32_e32 v142, v180, v142
	s_waitcnt lgkmcnt(0)
	v_mfma_f32_32x32x16_bf16 v[16:31], v[76:79], v[72:75], v[16:31]
	ds_read_b128 v[76:79], v155 offset:36864
	v_add_f32_e32 v143, v181, v143
	v_add_f32_e32 v142, v182, v142
	v_add_f32_e32 v143, v183, v143
	v_add_f32_e32 v142, v184, v142
	v_add_f32_e32 v143, v185, v143
	v_add_f32_e32 v142, v186, v142
	v_mfma_f32_32x32x16_bf16 v[0:15], v[82:85], v[72:75], v[0:15]
	ds_read_b128 v[72:75], v155 offset:32768
	v_add_f32_e32 v143, v187, v143
	v_add_f32_e32 v142, v188, v142
	v_add_f32_e32 v143, v189, v143
	v_add_f32_e32 v142, v143, v142
	v_add_f32_e32 v142, 0, v142
	v_add_f32_e32 v149, v142, v80
	s_waitcnt lgkmcnt(0)
	v_mfma_f32_32x32x16_bf16 v[16:31], v[72:75], v[68:71], v[16:31]
	ds_read_b128 v[72:75], v154 offset:36864
	s_cmp_lg_u32 s13, 0
	v_mfma_f32_32x32x16_bf16 v[0:15], v[76:79], v[68:71], v[0:15]
	ds_read_b128 v[68:71], v154 offset:32768
	s_waitcnt vmcnt(0)
	s_waitcnt vmcnt(0) lgkmcnt(0)
	s_barrier
	v_mfma_f32_32x32x16_bf16 v[16:31], v[68:71], v[64:67], v[16:31]
	v_mfma_f32_32x32x16_bf16 v[0:15], v[72:75], v[64:67], v[0:15]
	s_cbranch_scc1 .LBB0_236
	v_readfirstlane_b32 s98, v129
	v_readfirstlane_b32 s99, v130
	v_lshlrev_b32_e32 v206, 1, v192
	v_lshlrev_b32_e32 v210, 1, v120
	v_lshlrev_b32_e32 v222, 1, v122
	v_lshlrev_b32_e32 v227, 1, v124
	v_lshlrev_b32_e32 v228, 1, v126
	s_sub_i32 s10, 0x82, s13
	s_mov_b32 s19, 2
	s_movk_i32 s17, 0x5000
	s_mov_b32 s13, 0
	s_mov_b32 s2, 0xa000
.LBB0_223:
	s_add_i32 s3, s13, 32
	v_add3_u32 v153, s3, v133, v132
	v_add3_u32 v152, s3, v134, v132
	ds_read_b128 v[216:219], v153
	ds_read_b128 v[240:243], v152
	ds_read_b128 v[244:247], v153 offset:4096
	ds_read_b128 v[248:251], v152 offset:4096
	s_add_i32 s70, s19, 2
	s_mul_i32 s8, s70, 0x3000
	s_mul_hi_u32 s3, s70, 0x3000
	s_add_u32 s42, s5, s8
	s_addc_u32 s43, s11, s3
	s_lshl_b64 s[44:45], s[70:71], 7
	s_add_u32 s44, s12, s44
	s_addc_u32 s45, s16, s45
	s_add_i32 s3, s17, 32
	s_add_i32 s8, s3, s98
	s_mov_b32 m0, s8
	s_add_i32 s3, s3, s99
	global_load_lds_dwordx4 v206, s[42:43]
	s_mov_b32 m0, s3
	s_mov_b32 s18, s13
	global_load_lds_dwordx4 v210, s[42:43]
	s_add_i32 m0, s8, 0x2000
	s_add_i32 s8, s8, 0x3000
	global_load_lds_dwordx4 v222, s[42:43]
	s_mov_b32 m0, s8
	s_add_i32 s3, s3, 0x3000
	global_load_lds_dwordx4 v227, s[44:45]
	s_mov_b32 m0, s3
	s_nop 0
	global_load_lds_dwordx4 v228, s[44:45]
	s_add_i32 s8, s18, 32
	v_add_u32_e32 v64, s8, v131
	s_mov_b32 s13, s2
	s_mov_b64 s[2:3], -1
	s_andn2_b64 vcc, exec, s[28:29]
	v_add3_u32 v151, s8, v135, v132
	v_add3_u32 v150, s8, v138, v132
	v_add_u32_e32 v143, v64, v140
	v_add_u32_e32 v142, v64, v141
	s_cbranch_vccz .LBB0_225
	s_mov_b64 s[2:3], 0
	ds_read_b128 v[154:157], v151
	s_waitcnt lgkmcnt(4)
	v_mfma_f32_32x32x16_bf16 v[80:95], v[216:219], v[116:119], 0
	ds_read_b128 v[216:219], v151 offset:4096
	s_waitcnt lgkmcnt(4)
	v_mfma_f32_32x32x16_bf16 v[80:95], v[240:243], v[112:115], v[80:95]
	ds_read_b128 v[240:243], v150
	s_waitcnt lgkmcnt(4)
	v_mfma_f32_32x32x16_bf16 v[64:79], v[244:247], v[116:119], 0
	ds_read_b128 v[244:247], v150 offset:4096
	s_waitcnt lgkmcnt(4)
	v_mfma_f32_32x32x16_bf16 v[64:79], v[248:251], v[112:115], v[64:79]
	ds_read_b128 v[248:251], v143 offset:8192
	s_waitcnt lgkmcnt(4)
	v_mfma_f32_32x32x16_bf16 v[80:95], v[154:157], v[108:111], v[80:95]
	ds_read_b128 v[154:157], v143 offset:10240
	s_waitcnt lgkmcnt(4)
	v_mfma_f32_32x32x16_bf16 v[64:79], v[216:219], v[108:111], v[64:79]
	ds_read_b128 v[216:219], v142 offset:8192
	s_waitcnt lgkmcnt(4)
	v_mfma_f32_32x32x16_bf16 v[80:95], v[240:243], v[104:107], v[80:95]
	ds_read_b128 v[240:243], v142 offset:10240
	s_waitcnt lgkmcnt(4)
	v_mfma_f32_32x32x16_bf16 v[64:79], v[244:247], v[104:107], v[64:79]
	s_waitcnt lgkmcnt(3)
	v_mfma_f32_32x32x16_bf16 v[80:95], v[248:251], v[100:103], v[80:95]
	s_waitcnt lgkmcnt(2)
	v_mfma_f32_32x32x16_bf16 v[64:79], v[154:157], v[100:103], v[64:79]
	s_waitcnt lgkmcnt(1)
	v_mfma_f32_32x32x16_bf16 v[80:95], v[216:219], v[96:99], v[80:95]
	s_waitcnt lgkmcnt(0)
	v_mfma_f32_32x32x16_bf16 v[64:79], v[240:243], v[96:99], v[64:79]

.LBB0_230:
	s_add_i32 s48, s13, 32
	v_add_u32_e32 v142, s48, v139
	v_exp_f32_e32 v150, v32
	v_add_u32_e32 v32, v142, v148
	v_exp_f32_e32 v143, v48
	v_exp_f32_e32 v151, v49
	v_exp_f32_e32 v153, v50
	v_exp_f32_e32 v154, v51
	ds_read_b128 v[48:51], v32 offset:12288
	v_exp_f32_e32 v155, v52
	v_exp_f32_e32 v156, v53
	v_exp_f32_e32 v159, v54
	v_exp_f32_e32 v158, v55
	ds_read_b128 v[166:169], v32 offset:16384
	v_cvt_pk_bf16_f32 v52, v143, v151
	v_cvt_pk_bf16_f32 v53, v153, v154
	v_cvt_pk_bf16_f32 v54, v155, v156
	v_cvt_pk_bf16_f32 v55, v159, v158
	v_add_u32_e32 v32, v142, v147
	v_exp_f32_e32 v157, v56
	s_waitcnt lgkmcnt(0)
	v_mfma_f32_32x32x16_bf16 v[16:31], v[48:51], v[52:55], v[16:31]
	ds_read_b128 v[48:51], v32 offset:12288
	v_exp_f32_e32 v165, v57
	v_exp_f32_e32 v163, v58
	v_exp_f32_e32 v162, v59
	v_exp_f32_e32 v161, v60
	v_exp_f32_e32 v160, v61
	v_exp_f32_e32 v164, v63
	v_mfma_f32_32x32x16_bf16 v[0:15], v[166:169], v[52:55], v[0:15]
	v_exp_f32_e32 v166, v62
	v_cvt_pk_bf16_f32 v52, v157, v165
	v_cvt_pk_bf16_f32 v53, v163, v162
	v_cvt_pk_bf16_f32 v54, v161, v160
	v_cvt_pk_bf16_f32 v55, v166, v164
	v_exp_f32_e32 v152, v33
	ds_read_b128 v[56:59], v32 offset:16384
	s_waitcnt lgkmcnt(0)
	v_mfma_f32_32x32x16_bf16 v[16:31], v[48:51], v[52:55], v[16:31]
	v_add_u32_e32 v48, v142, v146
	v_exp_f32_e32 v172, v34
	v_exp_f32_e32 v170, v35
	ds_read_b128 v[32:35], v48 offset:12288
	v_exp_f32_e32 v169, v36
	v_exp_f32_e32 v168, v37
	v_exp_f32_e32 v167, v38
	v_exp_f32_e32 v173, v39
	v_exp_f32_e32 v171, v40
	v_cvt_pk_bf16_f32 v36, v150, v152
	v_cvt_pk_bf16_f32 v37, v172, v170
	v_cvt_pk_bf16_f32 v38, v169, v168
	v_cvt_pk_bf16_f32 v39, v167, v173
	ds_read_b128 v[48:51], v48 offset:16384
	v_add_u32_e32 v40, v142, v145
	v_mfma_f32_32x32x16_bf16 v[0:15], v[56:59], v[52:55], v[0:15]
	s_add_i32 s2, s19, 3
	s_mul_i32 s44, s2, 0x3000
	s_mul_hi_u32 s19, s2, 0x3000
	s_add_u32 s46, s5, s44
	v_exp_f32_e32 v179, v41
	v_exp_f32_e32 v177, v42
	v_exp_f32_e32 v176, v43
	s_waitcnt lgkmcnt(0)
	v_mfma_f32_32x32x16_bf16 v[16:31], v[32:35], v[36:39], v[16:31]
	ds_read_b128 v[32:35], v40 offset:12288
	v_exp_f32_e32 v175, v44
	v_exp_f32_e32 v174, v45
	v_exp_f32_e32 v180, v46
	v_exp_f32_e32 v178, v47
	s_addc_u32 s47, s11, s19
	s_cmp_lg_u32 32, -1
	s_cselect_b32 s19, 32, 0
	s_mov_b32 s3, s71
	s_add_i32 s19, s13, s19
	v_mfma_f32_32x32x16_bf16 v[0:15], v[48:51], v[36:39], v[0:15]
	v_cvt_pk_bf16_f32 v36, v171, v179
	v_cvt_pk_bf16_f32 v37, v177, v176
	v_cvt_pk_bf16_f32 v38, v175, v174
	v_cvt_pk_bf16_f32 v39, v180, v178
	s_lshl_b64 s[2:3], s[2:3], 7
	s_add_u32 s44, s12, s2
	ds_read_b128 v[40:43], v40 offset:16384
	s_waitcnt lgkmcnt(0)
	v_mfma_f32_32x32x16_bf16 v[16:31], v[32:35], v[36:39], v[16:31]
	s_addc_u32 s45, s16, s3
	s_add_i32 s2, s19, s98
	s_waitcnt vmcnt(0)
	s_waitcnt vmcnt(0)
	s_barrier
	s_mov_b32 m0, s2
	s_add_i32 vcc_lo, s17, 32
	v_add3_u32 v186, vcc_lo, v133, v132
	v_add3_u32 v185, vcc_lo, v134, v132
	ds_read_b128 v[216:219], v186
	ds_read_b128 v[240:243], v185
	ds_read_b128 v[244:247], v186 offset:4096
	ds_read_b128 v[248:251], v185 offset:4096
	global_load_lds_dwordx4 v206, s[46:47]
	s_add_i32 m0, s19, s99
	s_add_i32 s3, s2, 0x2000
	global_load_lds_dwordx4 v210, s[46:47]
	s_mov_b32 m0, s3
	s_add_i32 s3, s2, 0x3000
	global_load_lds_dwordx4 v222, s[46:47]
	s_mov_b32 m0, s3
	s_add_i32 s3, s19, s99
	global_load_lds_dwordx4 v227, s[44:45]
	s_add_i32 m0, s3, 0x3000
	v_mfma_f32_32x32x16_bf16 v[0:15], v[40:43], v[36:39], v[0:15]
	global_load_lds_dwordx4 v228, s[44:45]
	s_add_i32 s19, s17, 32
	v_add_u32_e32 v32, s19, v131
	s_mov_b64 s[2:3], -1
	s_andn2_b64 vcc, exec, s[28:29]
	v_add3_u32 v184, s19, v135, v132
	v_add3_u32 v183, s19, v138, v132
	v_add_u32_e32 v182, v32, v140
	v_add_u32_e32 v181, v32, v141
	s_cbranch_vccz .LBB0_232
	s_mov_b64 s[2:3], 0
	ds_read_b128 v[188:191], v184
	s_waitcnt lgkmcnt(4)
	v_mfma_f32_32x32x16_bf16 v[48:63], v[216:219], v[116:119], 0
	ds_read_b128 v[216:219], v184 offset:4096
	s_waitcnt lgkmcnt(4)
	v_mfma_f32_32x32x16_bf16 v[48:63], v[240:243], v[112:115], v[48:63]
	ds_read_b128 v[240:243], v183
	s_waitcnt lgkmcnt(4)
	v_mfma_f32_32x32x16_bf16 v[32:47], v[244:247], v[116:119], 0
	ds_read_b128 v[244:247], v183 offset:4096
	s_waitcnt lgkmcnt(4)
	v_mfma_f32_32x32x16_bf16 v[32:47], v[248:251], v[112:115], v[32:47]
	ds_read_b128 v[248:251], v182 offset:8192
	s_waitcnt lgkmcnt(4)
	v_mfma_f32_32x32x16_bf16 v[48:63], v[188:191], v[108:111], v[48:63]
	ds_read_b128 v[188:191], v182 offset:10240
	s_waitcnt lgkmcnt(4)
	v_mfma_f32_32x32x16_bf16 v[32:47], v[216:219], v[108:111], v[32:47]
	ds_read_b128 v[216:219], v181 offset:8192
	s_waitcnt lgkmcnt(4)
	v_mfma_f32_32x32x16_bf16 v[48:63], v[240:243], v[104:107], v[48:63]
	ds_read_b128 v[240:243], v181 offset:10240
	s_waitcnt lgkmcnt(4)
	v_mfma_f32_32x32x16_bf16 v[32:47], v[244:247], v[104:107], v[32:47]
	s_waitcnt lgkmcnt(3)
	v_mfma_f32_32x32x16_bf16 v[48:63], v[248:251], v[100:103], v[48:63]
	s_waitcnt lgkmcnt(2)
	v_mfma_f32_32x32x16_bf16 v[32:47], v[188:191], v[100:103], v[32:47]
	s_waitcnt lgkmcnt(1)
	v_mfma_f32_32x32x16_bf16 v[48:63], v[216:219], v[96:99], v[48:63]
	s_waitcnt lgkmcnt(0)
	v_mfma_f32_32x32x16_bf16 v[32:47], v[240:243], v[96:99], v[32:47]

	.amdhsa_kernel _Z10fwd_kernel6Params
		.amdhsa_group_segment_fixed_size 32
		.amdhsa_private_segment_fixed_size 0
		.amdhsa_kernarg_size 704
		.amdhsa_user_sgpr_count 2
		.amdhsa_user_sgpr_dispatch_ptr 0
		.amdhsa_user_sgpr_queue_ptr 0
		.amdhsa_user_sgpr_kernarg_segment_ptr 1
		.amdhsa_user_sgpr_dispatch_id 0
		.amdhsa_user_sgpr_kernarg_preload_length 0
		.amdhsa_user_sgpr_kernarg_preload_offset 0
		.amdhsa_user_sgpr_private_segment_size 0
		.amdhsa_uses_dynamic_stack 0
		.amdhsa_enable_private_segment 0
		.amdhsa_system_sgpr_workgroup_id_x 1
		.amdhsa_system_sgpr_workgroup_id_y 0
		.amdhsa_system_sgpr_workgroup_id_z 0
		.amdhsa_system_sgpr_workgroup_info 0
		.amdhsa_system_vgpr_workitem_id 2
		.amdhsa_next_free_vgpr 256
		.amdhsa_next_free_sgpr 100
		.amdhsa_accum_offset 256
		.amdhsa_reserve_vcc 1
		.amdhsa_float_round_mode_32 0
		.amdhsa_float_round_mode_16_64 0
		.amdhsa_float_denorm_mode_32 3
		.amdhsa_float_denorm_mode_16_64 3
		.amdhsa_dx10_clamp 1
		.amdhsa_ieee_mode 1
		.amdhsa_fp16_overflow 0
		.amdhsa_tg_split 0
		.amdhsa_exception_fp_ieee_invalid_op 0
		.amdhsa_exception_fp_denorm_src 0
		.amdhsa_exception_fp_ieee_div_zero 0
		.amdhsa_exception_fp_ieee_overflow 0
		.amdhsa_exception_fp_ieee_underflow 0
		.amdhsa_exception_fp_ieee_inexact 0
		.amdhsa_exception_int_div_zero 0
	.end_amdhsa_kernel

.Lfunc_end0:
	.size	_Z10fwd_kernel6Params, .Lfunc_end0-_Z10fwd_kernel6Params
	.set _Z10fwd_kernel6Params.num_vgpr, 256
	.set _Z10fwd_kernel6Params.num_agpr, 0
	.set _Z10fwd_kernel6Params.numbered_sgpr, 100
	.set _Z10fwd_kernel6Params.num_named_barrier, 0
	.set _Z10fwd_kernel6Params.private_seg_size, 0
	.set _Z10fwd_kernel6Params.uses_vcc, 1
	.set _Z10fwd_kernel6Params.uses_flat_scratch, 0
	.set _Z10fwd_kernel6Params.has_dyn_sized_stack, 0
	.set _Z10fwd_kernel6Params.has_recursion, 0
	.set _Z10fwd_kernel6Params.has_indirect_call, 0

amdhsa.kernels:
  - .agpr_count:     0
    .args:
      - .offset:         0
        .size:           448
        .value_kind:     by_value
      - .offset:         448
        .size:           4
        .value_kind:     hidden_block_count_x
      - .offset:         452
        .size:           4
        .value_kind:     hidden_block_count_y
      - .offset:         456
        .size:           4
        .value_kind:     hidden_block_count_z
      - .offset:         460
        .size:           2
        .value_kind:     hidden_group_size_x
      - .offset:         462
        .size:           2
        .value_kind:     hidden_group_size_y
      - .offset:         464
        .size:           2
        .value_kind:     hidden_group_size_z
      - .offset:         466
        .size:           2
        .value_kind:     hidden_remainder_x
      - .offset:         468
        .size:           2
        .value_kind:     hidden_remainder_y
      - .offset:         470
        .size:           2
        .value_kind:     hidden_remainder_z
      - .offset:         488
        .size:           8
        .value_kind:     hidden_global_offset_x
      - .offset:         496
        .size:           8
        .value_kind:     hidden_global_offset_y
      - .offset:         504
        .size:           8
        .value_kind:     hidden_global_offset_z
      - .offset:         512
        .size:           2
        .value_kind:     hidden_grid_dims
      - .offset:         536
        .size:           8
        .value_kind:     hidden_multigrid_sync_arg
      - .offset:         568
        .size:           4
        .value_kind:     hidden_dynamic_lds_size
    .group_segment_fixed_size: 32
    .kernarg_segment_align: 8
    .kernarg_segment_size: 704
    .language:       OpenCL C
    .language_version:
      - 2
      - 0
    .max_flat_workgroup_size: 256
    .name:           _Z10fwd_kernel6Params
    .private_segment_fixed_size: 0
    .sgpr_count:     106
    .sgpr_spill_count: 214
    .symbol:         _Z10fwd_kernel6Params.kd
    .uniform_work_group_size: 1
    .uses_dynamic_stack: false
    .vgpr_count:     256
    .vgpr_spill_count: 0
    .wavefront_size: 64
